# grid barrier: non-leader workgroups poll the top-level generation word directly (one hop less on the release path)
# baseline (speedup 1.0000x reference)
.LBB0_170:
	s_or_b64 exec, exec, s[6:7]
	v_cvt_f32_u32_e32 v4, v2
	s_waitcnt vmcnt(0)
	v_readfirstlane_b32 s0, v3
	v_sub_u32_e32 v3, 0, v2
	v_rcp_iflag_f32_e32 v4, v4
	v_add_u32_e32 v5, s0, v1
	v_mul_f32_e32 v4, 0x4f7ffffe, v4
	v_cvt_u32_f32_e32 v4, v4
	v_mul_lo_u32 v1, v3, v4
	v_mul_hi_u32 v1, v4, v1
	v_add_u32_e32 v1, v4, v1
	v_mul_hi_u32 v1, v5, v1
	v_mul_lo_u32 v3, v1, v2
	v_sub_u32_e32 v3, v5, v3
	v_add_u32_e32 v4, 1, v1
	v_cmp_ge_u32_e32 vcc, v3, v2
	s_nop 1
	v_cndmask_b32_e32 v1, v1, v4, vcc
	v_sub_u32_e32 v4, v3, v2
	v_cndmask_b32_e32 v3, v3, v4, vcc
	v_add_u32_e32 v4, 1, v1
	v_cmp_ge_u32_e32 vcc, v3, v2
	v_add_u32_e32 v3, 1, v5
	s_nop 0
	v_cndmask_b32_e32 v1, v1, v4, vcc
	v_mul_lo_u32 v4, v2, v1
	v_add_u32_e32 v2, v4, v2
	v_cmp_ne_u32_e32 vcc, v3, v2
	s_and_saveexec_b64 s[0:1], vcc
	s_xor_b64 s[6:7], exec, s[0:1]
	s_cbranch_execz .LBB0_184
	v_readlane_b32 s0, v254, 35
	v_readlane_b32 s1, v254, 36
	s_waitcnt lgkmcnt(0)
	s_nop 3
	global_load_dword v0, v131, s[0:1] sc1
	s_waitcnt vmcnt(0)
	v_cmp_eq_u32_e32 vcc, v0, v1
	s_and_saveexec_b64 s[8:9], vcc
	s_cbranch_execz .LBB0_183
	s_mov_b32 s0, 1
	s_mov_b64 s[10:11], 0
	s_branch .LBB0_174

.LBB0_178:
	v_readlane_b32 s12, v254, 35
	v_readlane_b32 s13, v254, 36
	s_add_i32 s0, s0, 1
	s_mov_b64 s[28:29], -1
	s_nop 2
	global_load_dword v0, v131, s[12:13] sc1
	s_waitcnt vmcnt(0)
	v_cmp_ne_u32_e32 vcc, v0, v1
	s_orn2_b64 s[18:19], vcc, exec
	s_branch .LBB0_173
